# C/B loops: s_setprio 1 around S and PV MFMA bursts
# speedup vs baseline: 1.0018x; 1.0018x over previous
; template <int MODE> __device__ __forceinline__ void attn_unit(FLAS unsigned char* lds, const Unit u) {
;     ...
;     for (int t = u.t_lo; t < u.t_hi; ++t) {
;         const int cur = (t - u.t_lo) & 1;
;         const bool more = (t + 1 < u.t_hi);
;         if (more) { kreg = *(const u32x4*)(ksrc + (size_t)(t + 1) * 64 * u.ldk);
; #pragma unroll
;             for (int i = 0; i < NVR; ++i) vreg[i] = *(const u32x4*)(vsrc + (size_t)i * 64 * MTOK + (t + 1) * 64); }
;         const int k0 = t * 64;
;         bool active = true;
;         if (MODE == 1) active = (t >= rstart) && (t < rstart + 8);
;         if (MODE == 2) active = (k0 + 63 >= q0w - 1024) && (k0 <= q0w + 31 + 1024);
;         if (active) {
;             f32x16 p0, p1;
;             bf16x8 kf[8];
;             { const FLAS unsigned char* kb = lds + L_K + cur * KBUF;
; #pragma unroll
;               for (int d0 = 0; d0 < 4; ++d0) { const int ko = (2 * d0 + hi) * 1024 + ((r32 ^ (2 * d0 + hi)) * 16); kf[2 * d0] = *(const FLAS bf16x8*)(kb + ko); kf[2 * d0 + 1] = *(const FLAS bf16x8*)(kb + ko + 512); } }
;             float cb = 0.f; bool zinit = false;
;             if (MODE == 0) { const int dmin = k0 - (q0w + 31), dmax = k0 + 63 - q0w;
;                 if (dmin >= 559) { cb = L[LUT_C + 600]; zinit = true; } else if (dmax <= -559) { cb = L[LUT_C - 600]; zinit = true; } }
;             if (zinit) {
;                 const f32x16 z16 = {0.f,0.f,0.f,0.f,0.f,0.f,0.f,0.f,0.f,0.f,0.f,0.f,0.f,0.f,0.f,0.f};
;                 FA_SB();
;                 p0 = __builtin_amdgcn_mfma_f32_32x32x16_bf16(kf[0], qr[0], z16, 0, 0, 0); p1 = __builtin_amdgcn_mfma_f32_32x32x16_bf16(kf[1], qr[0], z16, 0, 0, 0);
; #pragma unroll
;                 for (int d0 = 1; d0 < 4; ++d0) { p0 = __builtin_amdgcn_mfma_f32_32x32x16_bf16(kf[2 * d0], qr[d0], p0, 0, 0, 0); p1 = __builtin_amdgcn_mfma_f32_32x32x16_bf16(kf[2 * d0 + 1], qr[d0], p1, 0, 0, 0); }
;             } else {
;                 if (MODE == 0 || MODE == 2) { const FLAS float* lp = L + (k0 - q + LUT_C + 4 * hi);
; #pragma unroll
;                     for (int r = 0; r < 16; ++r) { p0[r] = lp[(r & 3) + 8 * (r >> 2)]; p1[r] = lp[32 + (r & 3) + 8 * (r >> 2)]; }
;                 } else { const FLAS float* lp = L + ((t - gi + 7) * 128 + 63 - qc + 4 * hi);
; #pragma unroll
;                     for (int r = 0; r < 16; ++r) { const int kc = (r & 3) + 8 * (r >> 2) + 4 * hi;
.LBB0_498:
	s_and_b32 s24, s8, 1
	s_add_i32 s9, s22, 63
	s_cmp_ge_i32 s9, s12
	s_cselect_b64 s[34:35], -1, 0
	s_cmp_le_i32 s22, s21
	s_cselect_b64 s[38:39], -1, 0
	s_and_b64 s[34:35], s[34:35], s[38:39]
	s_andn2_b64 vcc, exec, s[34:35]
	s_cbranch_vccnz .LBB0_506
	s_lshl_b32 s9, s24, 13
	s_add_i32 s9, s9, 0
	v_add3_u32 v32, s9, v139, v140
	ds_read_b128 v[88:91], v32
	ds_read_b128 v[92:95], v32 offset:512
	v_add3_u32 v32, s9, v141, v142
	ds_read_b128 v[102:105], v32
	ds_read_b128 v[106:109], v32 offset:512
	v_add3_u32 v32, s9, v143, v144
	ds_read_b128 v[110:113], v32
	ds_read_b128 v[114:117], v32 offset:512
	v_add3_u32 v32, s9, v145, v146
	ds_read_b128 v[118:121], v32
	ds_read_b128 v[122:125], v32 offset:512
	ds_read2_b32 v[32:33], v147 offset1:1
	ds_read2_b32 v[34:35], v147 offset0:2 offset1:3
	ds_read2_b32 v[36:37], v147 offset0:8 offset1:9
	ds_read2_b32 v[38:39], v147 offset0:10 offset1:11
	ds_read2_b32 v[48:49], v147 offset0:32 offset1:33
	ds_read2_b32 v[50:51], v147 offset0:34 offset1:35
	ds_read2_b32 v[52:53], v147 offset0:40 offset1:41
	ds_read2_b32 v[54:55], v147 offset0:42 offset1:43
	ds_read2_b32 v[40:41], v147 offset0:16 offset1:17
	ds_read2_b32 v[42:43], v147 offset0:18 offset1:19
	ds_read2_b32 v[44:45], v147 offset0:24 offset1:25
	ds_read2_b32 v[46:47], v147 offset0:26 offset1:27
	ds_read2_b32 v[56:57], v147 offset0:48 offset1:49
	ds_read2_b32 v[58:59], v147 offset0:50 offset1:51
	ds_read2_b32 v[60:61], v147 offset0:56 offset1:57
	ds_read2_b32 v[62:63], v147 offset0:58 offset1:59
	s_xor_b64 s[6:7], s[6:7], -1
	s_waitcnt lgkmcnt(4)
	s_setprio 1
	v_mfma_f32_32x32x16_bf16 v[32:47], v[88:91], v[64:67], v[32:47]
	s_mul_i32 s9, s24, 0x4800
	v_add_u32_e32 v149, s9, v138
	s_waitcnt lgkmcnt(0)
	v_mfma_f32_32x32x16_bf16 v[48:63], v[92:95], v[64:67], v[48:63]
	ds_read_b128 v[92:95], v149 offset:16384
	ds_read_b128 v[88:91], v149 offset:20992
	v_mfma_f32_32x32x16_bf16 v[32:47], v[102:105], v[68:71], v[32:47]
	v_mfma_f32_32x32x16_bf16 v[48:63], v[106:109], v[68:71], v[48:63]
	v_mfma_f32_32x32x16_bf16 v[32:47], v[110:113], v[72:75], v[32:47]
	v_mfma_f32_32x32x16_bf16 v[48:63], v[114:117], v[72:75], v[48:63]
	v_mfma_f32_32x32x16_bf16 v[32:47], v[118:121], v[76:79], v[32:47]
	v_mfma_f32_32x32x16_bf16 v[48:63], v[122:125], v[76:79], v[48:63]
	s_setprio 0
	s_and_b32 s8, s8, 3
	s_cmp_lg_u32 s8, 0
	s_cselect_b64 s[8:9], -1, 0
	v_sub_f32_e32 v102, 0, v148
	s_and_b64 s[8:9], s[6:7], s[8:9]
	s_nop 5
	v_add_f32_e32 v132, v102, v32
	v_add_f32_e32 v133, v102, v33
	v_add_f32_e32 v120, v102, v48
	v_add_f32_e32 v121, v102, v49
	v_add_f32_e32 v130, v102, v34
	v_add_f32_e32 v131, v102, v35
	v_add_f32_e32 v116, v102, v50
	v_add_f32_e32 v117, v102, v51
	v_add_f32_e32 v128, v102, v36
	v_add_f32_e32 v129, v102, v37
	v_add_f32_e32 v114, v102, v52
	v_add_f32_e32 v115, v102, v53
	v_add_f32_e32 v126, v102, v38
	v_add_f32_e32 v127, v102, v39
	v_add_f32_e32 v110, v102, v54
	v_add_f32_e32 v111, v102, v55
	v_add_f32_e32 v124, v102, v40
	v_add_f32_e32 v125, v102, v41
	v_add_f32_e32 v108, v102, v56
	v_add_f32_e32 v109, v102, v57
	v_add_f32_e32 v122, v102, v42
	v_add_f32_e32 v123, v102, v43
	v_add_f32_e32 v106, v102, v58
	v_add_f32_e32 v107, v102, v59
	v_add_f32_e32 v118, v102, v44
	v_add_f32_e32 v119, v102, v45
	v_add_f32_e32 v104, v102, v60
	v_add_f32_e32 v105, v102, v61
	v_add_f32_e32 v112, v102, v46
	v_add_f32_e32 v113, v102, v47
	v_add_f32_e32 v103, v102, v63
	v_add_f32_e32 v102, v102, v62
	s_and_b64 vcc, exec, s[8:9]
	s_mov_b32 s25, 0x41000000
	s_cbranch_vccnz .LBB0_507
; __device__ __forceinline__ float xhalf_max(float m) { unsigned a = __builtin_bit_cast(unsigned, m), b = a; xswap(a, b); return __builtin_fmaxf(__builtin_bit_cast(float, a), __builtin_bit_cast(float, b)); }
; template <int MODE> __device__ __forceinline__ void attn_unit(FLAS unsigned char* lds, const Unit u) {
;     ...
;             if (first || (((t - u.t_lo) & 3) == 0)) {
;             float rm = __builtin_fmaxf(p0[0], p1[0]);
; #pragma unroll
;             for (int r = 1; r < 16; ++r) rm = __builtin_fmaxf(rm, __builtin_fmaxf(p0[r], p1[r]));
;             rm = xhalf_max(rm);
;             if (first) {
;                 const float dl = __builtin_fmaxf(rm, -1000.0f); mrun = dl;
; #pragma unroll
;                 for (int r = 0; r < 16; ++r) { p0[r] = p0[r] - dl; p1[r] = p1[r] - dl; }
;                 first = false;
;             } else if (__any(rm > 8.0f)) { const float dl = __builtin_fmaxf(rm, 0.0f); const float f = __builtin_amdgcn_exp2f(-dl); mrun += dl; lsum *= f;
; #pragma unroll
;                 for (int i = 0; i < NDB; ++i) o[i] = o[i] * f;
; #pragma unroll
;                 for (int r = 0; r < 16; ++r) { p0[r] = p0[r] - dl; p1[r] = p1[r] - dl; } }
	v_max_f32_e32 v32, v121, v121
	v_max_f32_e32 v33, v133, v133
	v_max_f32_e32 v32, v33, v32
	v_max_f32_e32 v33, v116, v116
	v_max_f32_e32 v34, v130, v130
	v_max_f32_e32 v33, v34, v33
	v_max_f32_e32 v34, v117, v117
	v_max_f32_e32 v35, v131, v131
	v_max3_f32 v32, v132, v120, v32
	v_max_f32_e32 v34, v35, v34
	v_max3_f32 v32, v32, v33, v34
	v_max_f32_e32 v33, v114, v114
	v_max_f32_e32 v34, v128, v128
	v_max_f32_e32 v33, v34, v33
	v_max_f32_e32 v34, v115, v115
	v_max_f32_e32 v35, v129, v129
	v_max_f32_e32 v34, v35, v34
	v_max3_f32 v32, v32, v33, v34
	v_max_f32_e32 v33, v110, v110
	v_max_f32_e32 v34, v126, v126
	v_max_f32_e32 v33, v34, v33
	v_max_f32_e32 v34, v111, v111
	v_max_f32_e32 v35, v127, v127
	v_max_f32_e32 v34, v35, v34
	v_max3_f32 v32, v32, v33, v34
	v_max_f32_e32 v33, v108, v108
	v_max_f32_e32 v34, v124, v124
	v_max_f32_e32 v33, v34, v33
	v_max_f32_e32 v34, v109, v109
	v_max_f32_e32 v35, v125, v125
	v_max_f32_e32 v34, v35, v34
	v_max3_f32 v32, v32, v33, v34
	v_max_f32_e32 v33, v106, v106
	v_max_f32_e32 v34, v122, v122
	v_max_f32_e32 v33, v34, v33
	v_max_f32_e32 v34, v107, v107
	v_max_f32_e32 v35, v123, v123
	v_max_f32_e32 v34, v35, v34
	v_max3_f32 v32, v32, v33, v34
	v_max_f32_e32 v33, v104, v104
	v_max_f32_e32 v34, v118, v118
	v_max_f32_e32 v33, v34, v33
	v_max_f32_e32 v34, v105, v105
	v_max_f32_e32 v35, v119, v119
	v_max_f32_e32 v34, v35, v34
	v_max3_f32 v32, v32, v33, v34
	v_max_f32_e32 v33, v102, v102
	v_max_f32_e32 v34, v112, v112
	v_max_f32_e32 v33, v34, v33
	v_max_f32_e32 v34, v103, v103
	v_max_f32_e32 v35, v113, v113
	v_max_f32_e32 v34, v35, v34
	v_max3_f32 v32, v32, v33, v34
	v_mov_b32_e32 v33, v32
	s_nop 1
	v_permlane32_swap_b32 v32, v33
	s_nop 1
	s_mov_b64 s[8:9], -1
	v_max_f32_e32 v33, v33, v33
	v_max_f32_e32 v32, v32, v32
	v_max_f32_e32 v164, v32, v33
	s_and_b64 vcc, exec, s[6:7]
	s_movk_i32 s38, 0x87f
	s_mov_b64 s[34:35], 0x800
	s_cbranch_vccz .LBB0_503
	v_cmp_lt_f32_e32 vcc, s25, v164
	s_cbranch_vccz .LBB0_508
	v_max_f32_e32 v32, v164, v164
	v_max_f32_e32 v167, 0, v32
	v_exp_f32_e64 v184, -v167
	v_add_f32_e32 v148, v148, v167
	v_sub_f32_e32 v166, v132, v167
	v_sub_f32_e32 v165, v133, v167
	v_pk_mul_f32 v[62:63], v[30:31], v[184:185] op_sel_hi:[1,0]
	v_pk_mul_f32 v[60:61], v[28:29], v[184:185] op_sel_hi:[1,0]
	v_pk_mul_f32 v[58:59], v[26:27], v[184:185] op_sel_hi:[1,0]
	v_pk_mul_f32 v[56:57], v[24:25], v[184:185] op_sel_hi:[1,0]
	v_pk_mul_f32 v[54:55], v[22:23], v[184:185] op_sel_hi:[1,0]
	v_pk_mul_f32 v[52:53], v[20:21], v[184:185] op_sel_hi:[1,0]
	v_pk_mul_f32 v[50:51], v[18:19], v[184:185] op_sel_hi:[1,0]
	v_pk_mul_f32 v[48:49], v[16:17], v[184:185] op_sel_hi:[1,0]
	v_pk_mul_f32 v[46:47], v[14:15], v[184:185] op_sel_hi:[1,0]
	v_pk_mul_f32 v[44:45], v[12:13], v[184:185] op_sel_hi:[1,0]
	v_pk_mul_f32 v[42:43], v[10:11], v[184:185] op_sel_hi:[1,0]
	v_pk_mul_f32 v[40:41], v[8:9], v[184:185] op_sel_hi:[1,0]
	v_pk_mul_f32 v[38:39], v[6:7], v[184:185] op_sel_hi:[1,0]
	v_pk_mul_f32 v[36:37], v[4:5], v[184:185] op_sel_hi:[1,0]
	v_pk_mul_f32 v[34:35], v[2:3], v[184:185] op_sel_hi:[1,0]
	v_pk_mul_f32 v[32:33], v[0:1], v[184:185] op_sel_hi:[1,0]
	v_sub_f32_e32 v163, v130, v167
	v_sub_f32_e32 v162, v131, v167
	v_sub_f32_e32 v161, v128, v167
	v_sub_f32_e32 v160, v129, v167
	v_sub_f32_e32 v159, v126, v167
	v_sub_f32_e32 v158, v127, v167
	v_sub_f32_e32 v157, v124, v167
	v_sub_f32_e32 v156, v125, v167
	v_sub_f32_e32 v155, v122, v167
	v_sub_f32_e32 v154, v123, v167
	v_sub_f32_e32 v153, v118, v167
	v_sub_f32_e32 v152, v119, v167
	v_sub_f32_e32 v151, v112, v167
	v_sub_f32_e32 v150, v113, v167
	v_sub_f32_e32 v182, v120, v167
	v_sub_f32_e32 v181, v121, v167
	v_sub_f32_e32 v180, v116, v167
	v_sub_f32_e32 v179, v117, v167
	v_sub_f32_e32 v178, v114, v167
	v_sub_f32_e32 v177, v115, v167
	v_sub_f32_e32 v176, v110, v167
	v_sub_f32_e32 v175, v111, v167
	v_sub_f32_e32 v174, v108, v167
	v_sub_f32_e32 v173, v109, v167
	v_sub_f32_e32 v172, v106, v167
	v_sub_f32_e32 v171, v107, v167
	v_sub_f32_e32 v170, v104, v167
	v_sub_f32_e32 v169, v105, v167
	v_sub_f32_e32 v168, v102, v167
	v_sub_f32_e32 v167, v103, v167
	v_mul_f32_e32 v183, v137, v184
	s_mov_b64 s[8:9], 0

; #define FLAS __attribute__((address_space(3)))
; #define FA_SB() __builtin_amdgcn_sched_barrier(0)
; __device__ __forceinline__ unsigned cvtpk(float lo, float hi) { f32x2_t v = {lo, hi}; bf16x2_t b = __builtin_convertvector(v, bf16x2_t); return __builtin_bit_cast(unsigned, b); }
; template <int MODE> __device__ __forceinline__ void attn_unit(FLAS unsigned char* lds, const Unit u) {
;     ...
;             float ps = 0.f;
; #pragma unroll
;             for (int r = 0; r < 16; ++r) { p0[r] = __builtin_amdgcn_exp2f(p0[r]); p1[r] = __builtin_amdgcn_exp2f(p1[r]); ps += p0[r] + p1[r]; }
;             lsum += ps;
;             u32x4 pw[4];
;             pw[0] = (u32x4){cvtpk(p0[0], p0[1]), cvtpk(p0[2], p0[3]), cvtpk(p0[4], p0[5]), cvtpk(p0[6], p0[7])};
;             pw[1] = (u32x4){cvtpk(p0[8], p0[9]), cvtpk(p0[10], p0[11]), cvtpk(p0[12], p0[13]), cvtpk(p0[14], p0[15])};
;             pw[2] = (u32x4){cvtpk(p1[0], p1[1]), cvtpk(p1[2], p1[3]), cvtpk(p1[4], p1[5]), cvtpk(p1[6], p1[7])};
;             pw[3] = (u32x4){cvtpk(p1[8], p1[9]), cvtpk(p1[10], p1[11]), cvtpk(p1[12], p1[13]), cvtpk(p1[14], p1[15])};
;             FA_SB();
; #pragma unroll
;             for (int s = 0; s < 4; ++s) {
;                 if (s < 3) {
; #pragma unroll
;                     for (int db = 0; db < NDB; ++db) vf[(s + 1) & 1][db] = *(const FLAS u32x4*)(vb + db * 32 * VPITCH + (s + 1) * 32); }
; #pragma unroll
;                 for (int db = 0; db < NDB; ++db) o[db] = __builtin_amdgcn_mfma_f32_32x32x16_bf16(__builtin_bit_cast(bf16x8, vf[s & 1][db]), __builtin_bit_cast(bf16x8, pw[s]), o[db], 0, 0, 0);
;                 FA_SB();
;             }
.LBB0_508:
	v_exp_f32_e32 v132, v132
	v_exp_f32_e32 v133, v133
	v_exp_f32_e32 v130, v130
	v_exp_f32_e32 v131, v131
	v_add_f32_e32 v61, v132, v133
	v_cvt_pk_bf16_f32 v32, v132, v133
	v_exp_f32_e32 v128, v128
	v_add_f32_e32 v61, v130, v61
	v_exp_f32_e32 v129, v129
	v_add_f32_e32 v61, v131, v61
	v_cvt_pk_bf16_f32 v33, v130, v131
	v_exp_f32_e32 v126, v126
	v_add_f32_e32 v61, v128, v61
	v_exp_f32_e32 v127, v127
	v_add_f32_e32 v61, v129, v61
	v_cvt_pk_bf16_f32 v34, v128, v129
	v_exp_f32_e32 v124, v124
	v_add_f32_e32 v61, v126, v61
	v_exp_f32_e32 v125, v125
	v_add_f32_e32 v61, v127, v61
	v_cvt_pk_bf16_f32 v35, v126, v127
	v_exp_f32_e32 v122, v122
	v_add_f32_e32 v61, v124, v61
	v_exp_f32_e32 v123, v123
	v_add_f32_e32 v61, v125, v61
	v_cvt_pk_bf16_f32 v36, v124, v125
	v_exp_f32_e32 v118, v118
	v_add_f32_e32 v61, v122, v61
	v_exp_f32_e32 v119, v119
	v_add_f32_e32 v61, v123, v61
	v_cvt_pk_bf16_f32 v37, v122, v123
	v_exp_f32_e32 v112, v112
	v_add_f32_e32 v61, v118, v61
	v_exp_f32_e32 v113, v113
	v_add_f32_e32 v61, v119, v61
	v_cvt_pk_bf16_f32 v38, v118, v119
	v_exp_f32_e32 v120, v120
	v_add_f32_e32 v61, v112, v61
	v_exp_f32_e32 v121, v121
	v_add_f32_e32 v61, v113, v61
	v_cvt_pk_bf16_f32 v39, v112, v113
	v_exp_f32_e32 v116, v116
	v_add_f32_e32 v61, v120, v61
	v_exp_f32_e32 v117, v117
	v_add_f32_e32 v61, v121, v61
	v_cvt_pk_bf16_f32 v40, v120, v121
	v_exp_f32_e32 v114, v114
	v_add_f32_e32 v61, v116, v61
	v_exp_f32_e32 v115, v115
	v_add_f32_e32 v61, v117, v61
	v_cvt_pk_bf16_f32 v41, v116, v117
	v_exp_f32_e32 v110, v110
	v_add_f32_e32 v61, v114, v61
	v_exp_f32_e32 v111, v111
	v_add_f32_e32 v61, v115, v61
	v_cvt_pk_bf16_f32 v42, v114, v115
	v_exp_f32_e32 v108, v108
	v_add_f32_e32 v61, v110, v61
	v_exp_f32_e32 v109, v109
	v_add_f32_e32 v61, v111, v61
	v_cvt_pk_bf16_f32 v43, v110, v111
	v_exp_f32_e32 v106, v106
	v_add_f32_e32 v61, v108, v61
	v_exp_f32_e32 v107, v107
	v_add_f32_e32 v61, v109, v61
	v_cvt_pk_bf16_f32 v44, v108, v109
	v_exp_f32_e32 v104, v104
	v_add_f32_e32 v61, v106, v61
	v_exp_f32_e32 v105, v105
	v_add_f32_e32 v61, v107, v61
	v_cvt_pk_bf16_f32 v45, v106, v107
	v_exp_f32_e32 v102, v102
	v_add_f32_e32 v61, v104, v61
	v_exp_f32_e32 v103, v103
	v_add_f32_e32 v61, v105, v61
	v_cvt_pk_bf16_f32 v46, v104, v105
	v_add_f32_e32 v61, v102, v61
	v_add_f32_e32 v61, v103, v61
	v_cvt_pk_bf16_f32 v47, v102, v103
	s_waitcnt lgkmcnt(1)
	s_setprio 1
	v_mfma_f32_32x32x16_bf16 v[0:15], v[92:95], v[32:35], v[0:15]
	ds_read_b128 v[48:51], v149 offset:16416
	ds_read_b128 v[52:55], v149 offset:21024
	s_waitcnt lgkmcnt(2)
	v_mfma_f32_32x32x16_bf16 v[16:31], v[88:91], v[32:35], v[16:31]
	s_waitcnt lgkmcnt(1)
	v_mfma_f32_32x32x16_bf16 v[0:15], v[48:51], v[36:39], v[0:15]
	ds_read_b128 v[32:35], v149 offset:16448
	ds_read_b128 v[48:51], v149 offset:21056
	s_waitcnt lgkmcnt(2)
	v_mfma_f32_32x32x16_bf16 v[16:31], v[52:55], v[36:39], v[16:31]
	s_waitcnt lgkmcnt(1)
	v_mfma_f32_32x32x16_bf16 v[0:15], v[32:35], v[40:43], v[0:15]
	ds_read_b128 v[32:35], v149 offset:16480
	ds_read_b128 v[36:39], v149 offset:21088
	s_waitcnt lgkmcnt(2)
	v_mfma_f32_32x32x16_bf16 v[16:31], v[48:51], v[40:43], v[16:31]
	s_waitcnt lgkmcnt(1)
	v_mfma_f32_32x32x16_bf16 v[0:15], v[32:35], v[44:47], v[0:15]
	s_waitcnt lgkmcnt(0)
	v_mfma_f32_32x32x16_bf16 v[16:31], v[36:39], v[44:47], v[16:31]
	s_setprio 0
	v_add_f32_e32 v137, v137, v61
	s_mov_b64 s[6:7], 0
	s_andn2_b64 vcc, exec, s[4:5]
	s_cbranch_vccnz .LBB0_510

; template <int MODE> __device__ __forceinline__ void attn_unit(FLAS unsigned char* lds, const Unit u) {
;     ...
;     for (int t = u.t_lo; t < u.t_hi; ++t) {
;         const int cur = (t - u.t_lo) & 1;
;         const bool more = (t + 1 < u.t_hi);
;         if (more) { kreg = *(const u32x4*)(ksrc + (size_t)(t + 1) * 64 * u.ldk);
; #pragma unroll
;             for (int i = 0; i < NVR; ++i) vreg[i] = *(const u32x4*)(vsrc + (size_t)i * 64 * MTOK + (t + 1) * 64); }
;         const int k0 = t * 64;
;         bool active = true;
;         if (MODE == 1) active = (t >= rstart) && (t < rstart + 8);
;         if (MODE == 2) active = (k0 + 63 >= q0w - 1024) && (k0 <= q0w + 31 + 1024);
;         if (active) {
;             f32x16 p0, p1;
;             bf16x8 kf[8];
;             { const FLAS unsigned char* kb = lds + L_K + cur * KBUF;
; #pragma unroll
;               for (int d0 = 0; d0 < 4; ++d0) { const int ko = (2 * d0 + hi) * 1024 + ((r32 ^ (2 * d0 + hi)) * 16); kf[2 * d0] = *(const FLAS bf16x8*)(kb + ko); kf[2 * d0 + 1] = *(const FLAS bf16x8*)(kb + ko + 512); } }
;             float cb = 0.f; bool zinit = false;
;             if (MODE == 0) { const int dmin = k0 - (q0w + 31), dmax = k0 + 63 - q0w;
;                 if (dmin >= 559) { cb = L[LUT_C + 600]; zinit = true; } else if (dmax <= -559) { cb = L[LUT_C - 600]; zinit = true; } }
;             if (zinit) {
;                 const f32x16 z16 = {0.f,0.f,0.f,0.f,0.f,0.f,0.f,0.f,0.f,0.f,0.f,0.f,0.f,0.f,0.f,0.f};
;                 FA_SB();
;                 p0 = __builtin_amdgcn_mfma_f32_32x32x16_bf16(kf[0], qr[0], z16, 0, 0, 0); p1 = __builtin_amdgcn_mfma_f32_32x32x16_bf16(kf[1], qr[0], z16, 0, 0, 0);
; #pragma unroll
;                 for (int d0 = 1; d0 < 4; ++d0) { p0 = __builtin_amdgcn_mfma_f32_32x32x16_bf16(kf[2 * d0], qr[d0], p0, 0, 0, 0); p1 = __builtin_amdgcn_mfma_f32_32x32x16_bf16(kf[2 * d0 + 1], qr[d0], p1, 0, 0, 0); }
;             } else {
;                 if (MODE == 0 || MODE == 2) { const FLAS float* lp = L + (k0 - q + LUT_C + 4 * hi);
; #pragma unroll
;                     for (int r = 0; r < 16; ++r) { p0[r] = lp[(r & 3) + 8 * (r >> 2)]; p1[r] = lp[32 + (r & 3) + 8 * (r >> 2)]; }
;                 } else { const FLAS float* lp = L + ((t - gi + 7) * 128 + 63 - qc + 4 * hi);
; #pragma unroll
;                     for (int r = 0; r < 16; ++r) { const int kc = (r & 3) + 8 * (r >> 2) + 4 * hi;
.LBB0_530:
	s_and_b32 s21, s14, 1
	s_cmp_ge_i32 s14, s26
	s_cselect_b64 vcc, -1, 0
	s_cmp_lt_i32 s14, s12
	s_cselect_b64 s[28:29], -1, 0
	s_and_b64 s[28:29], vcc, s[28:29]
	s_andn2_b64 vcc, exec, s[28:29]
	s_cbranch_vccnz .LBB0_539
	s_lshl_b32 s15, s21, 13
	s_add_i32 s15, s15, 0
	v_add3_u32 v32, s15, v138, v139
	ds_read_b128 v[88:91], v32
	ds_read_b128 v[92:95], v32 offset:512
	v_add3_u32 v32, s15, v140, v141
	ds_read_b128 v[102:105], v32
	ds_read_b128 v[106:109], v32 offset:512
	v_add3_u32 v32, s15, v142, v143
	ds_read_b128 v[110:113], v32
	ds_read_b128 v[114:117], v32 offset:512
	v_add3_u32 v32, s15, v144, v145
	ds_read_b128 v[118:121], v32
	ds_read_b128 v[122:125], v32 offset:512
	ds_read2_b32 v[32:33], v147 offset1:1
	ds_read2_b32 v[34:35], v147 offset0:2 offset1:3
	ds_read2_b32 v[36:37], v147 offset0:8 offset1:9
	ds_read2_b32 v[38:39], v147 offset0:10 offset1:11
	ds_read2_b32 v[48:49], v147 offset0:32 offset1:33
	ds_read2_b32 v[50:51], v147 offset0:34 offset1:35
	ds_read2_b32 v[52:53], v147 offset0:40 offset1:41
	ds_read2_b32 v[54:55], v147 offset0:42 offset1:43
	ds_read2_b32 v[40:41], v147 offset0:16 offset1:17
	ds_read2_b32 v[42:43], v147 offset0:18 offset1:19
	ds_read2_b32 v[44:45], v147 offset0:24 offset1:25
	ds_read2_b32 v[46:47], v147 offset0:26 offset1:27
	ds_read2_b32 v[56:57], v147 offset0:48 offset1:49
	ds_read2_b32 v[58:59], v147 offset0:50 offset1:51
	ds_read2_b32 v[60:61], v147 offset0:56 offset1:57
	ds_read2_b32 v[62:63], v147 offset0:58 offset1:59
	s_xor_b64 s[22:23], s[22:23], -1
	s_waitcnt lgkmcnt(14)
	v_cndmask_b32_e64 v34, v242, v34, s[66:67]
	v_cndmask_b32_e64 v33, v242, v33, s[68:69]
	v_cndmask_b32_e64 v32, v242, v32, s[70:71]
	v_cndmask_b32_e64 v35, v242, v35, s[64:65]
	s_waitcnt lgkmcnt(13)
	v_cndmask_b32_e64 v36, v242, v36, s[62:63]
	v_cndmask_b32_e64 v37, v242, v37, s[60:61]
	s_waitcnt lgkmcnt(12)
	v_cndmask_b32_e64 v38, v242, v38, s[58:59]
	v_cndmask_b32_e64 v39, v242, v39, s[56:57]
	s_waitcnt lgkmcnt(7)
	v_cndmask_b32_e64 v40, v242, v40, s[54:55]
	v_cndmask_b32_e64 v41, v242, v41, s[52:53]
	s_waitcnt lgkmcnt(6)
	v_cndmask_b32_e64 v42, v242, v42, s[50:51]
	v_cndmask_b32_e64 v43, v242, v43, s[48:49]
	s_waitcnt lgkmcnt(5)
	v_cndmask_b32_e64 v44, v242, v44, s[46:47]
	v_cndmask_b32_e64 v45, v242, v45, s[44:45]
	s_waitcnt lgkmcnt(4)
	v_cndmask_b32_e64 v46, v242, v46, s[42:43]
	v_cndmask_b32_e64 v47, v242, v47, s[40:41]
	v_cndmask_b32_e64 v50, v242, v50, s[4:5]
	v_cndmask_b32_e64 v49, v242, v49, s[6:7]
	v_cndmask_b32_e64 v48, v242, v48, s[8:9]
	v_cndmask_b32_e64 v51, v242, v51, s[96:97]
	v_cndmask_b32_e64 v52, v242, v52, s[94:95]
	v_cndmask_b32_e64 v53, v242, v53, s[92:93]
	v_cndmask_b32_e64 v54, v242, v54, s[90:91]
	v_cndmask_b32_e64 v55, v242, v55, s[88:89]
	s_waitcnt lgkmcnt(3)
	v_cndmask_b32_e64 v56, v242, v56, s[86:87]
	v_cndmask_b32_e64 v57, v242, v57, s[84:85]
	s_waitcnt lgkmcnt(2)
	v_cndmask_b32_e64 v58, v242, v58, s[82:83]
	v_cndmask_b32_e64 v59, v242, v59, s[80:81]
	s_waitcnt lgkmcnt(1)
	v_cndmask_b32_e64 v60, v242, v60, s[78:79]
	v_cndmask_b32_e64 v61, v242, v61, s[76:77]
	s_waitcnt lgkmcnt(0)
	v_cndmask_b32_e64 v62, v242, v62, s[74:75]
	v_cndmask_b32_e64 v63, v242, v63, s[72:73]
	s_setprio 1
	v_mfma_f32_32x32x16_bf16 v[32:47], v[88:91], v[64:67], v[32:47]
	s_mul_i32 s15, s21, 0x4800
	v_add_u32_e32 v149, s15, v137
	v_mfma_f32_32x32x16_bf16 v[48:63], v[92:95], v[64:67], v[48:63]
	ds_read_b128 v[92:95], v149 offset:16384
	ds_read_b128 v[88:91], v149 offset:20992
	v_mfma_f32_32x32x16_bf16 v[32:47], v[102:105], v[68:71], v[32:47]
	v_mfma_f32_32x32x16_bf16 v[48:63], v[106:109], v[68:71], v[48:63]
	v_mfma_f32_32x32x16_bf16 v[32:47], v[110:113], v[72:75], v[32:47]
	v_mfma_f32_32x32x16_bf16 v[48:63], v[114:117], v[72:75], v[48:63]
	v_mfma_f32_32x32x16_bf16 v[32:47], v[118:121], v[76:79], v[32:47]
	v_mfma_f32_32x32x16_bf16 v[48:63], v[122:125], v[76:79], v[48:63]
	s_setprio 0
	s_and_b32 s14, s14, 3
	s_cmp_lg_u32 s14, 0
	s_cselect_b64 s[14:15], -1, 0
	v_sub_f32_e32 v102, 0, v148
	s_and_b64 s[14:15], s[22:23], s[14:15]
	s_nop 5
	v_add_f32_e32 v132, v102, v32
	v_add_f32_e32 v133, v102, v33
	v_add_f32_e32 v120, v102, v48
	v_add_f32_e32 v121, v102, v49
	v_add_f32_e32 v130, v102, v34
	v_add_f32_e32 v131, v102, v35
	v_add_f32_e32 v116, v102, v50
	v_add_f32_e32 v117, v102, v51
	v_add_f32_e32 v128, v102, v36
	v_add_f32_e32 v129, v102, v37
	v_add_f32_e32 v114, v102, v52
	v_add_f32_e32 v115, v102, v53
	v_add_f32_e32 v126, v102, v38
	v_add_f32_e32 v127, v102, v39
	v_add_f32_e32 v110, v102, v54
	v_add_f32_e32 v111, v102, v55
	v_add_f32_e32 v124, v102, v40
	v_add_f32_e32 v125, v102, v41
	v_add_f32_e32 v108, v102, v56
	v_add_f32_e32 v109, v102, v57
	v_add_f32_e32 v122, v102, v42
	v_add_f32_e32 v123, v102, v43
	v_add_f32_e32 v106, v102, v58
	v_add_f32_e32 v107, v102, v59
	v_add_f32_e32 v118, v102, v44
	v_add_f32_e32 v119, v102, v45
	v_add_f32_e32 v104, v102, v60
	v_add_f32_e32 v105, v102, v61
	v_add_f32_e32 v112, v102, v46
	v_add_f32_e32 v113, v102, v47
	v_add_f32_e32 v103, v102, v63
	v_add_f32_e32 v102, v102, v62
	s_and_b64 vcc, exec, s[14:15]
	s_cbranch_vccnz .LBB0_538
; __device__ __forceinline__ float xhalf_max(float m) { unsigned a = __builtin_bit_cast(unsigned, m), b = a; xswap(a, b); return __builtin_fmaxf(__builtin_bit_cast(float, a), __builtin_bit_cast(float, b)); }
; template <int MODE> __device__ __forceinline__ void attn_unit(FLAS unsigned char* lds, const Unit u) {
;     ...
;             if (first || (((t - u.t_lo) & 3) == 0)) {
;             float rm = __builtin_fmaxf(p0[0], p1[0]);
; #pragma unroll
;             for (int r = 1; r < 16; ++r) rm = __builtin_fmaxf(rm, __builtin_fmaxf(p0[r], p1[r]));
;             rm = xhalf_max(rm);
;             if (first) {
;                 const float dl = __builtin_fmaxf(rm, -1000.0f); mrun = dl;
; #pragma unroll
;                 for (int r = 0; r < 16; ++r) { p0[r] = p0[r] - dl; p1[r] = p1[r] - dl; }
;                 first = false;
;             } else if (__any(rm > 8.0f)) { const float dl = __builtin_fmaxf(rm, 0.0f); const float f = __builtin_amdgcn_exp2f(-dl); mrun += dl; lsum *= f;
; #pragma unroll
;                 for (int i = 0; i < NDB; ++i) o[i] = o[i] * f;
; #pragma unroll
;                 for (int r = 0; r < 16; ++r) { p0[r] = p0[r] - dl; p1[r] = p1[r] - dl; } }
	v_max_f32_e32 v32, v121, v121
	v_max_f32_e32 v33, v133, v133
	v_max_f32_e32 v32, v33, v32
	v_max_f32_e32 v33, v116, v116
	v_max_f32_e32 v34, v130, v130
	v_max_f32_e32 v33, v34, v33
	v_max_f32_e32 v34, v117, v117
	v_max_f32_e32 v35, v131, v131
	v_max3_f32 v32, v132, v120, v32
	v_max_f32_e32 v34, v35, v34
	v_max3_f32 v32, v32, v33, v34
	v_max_f32_e32 v33, v114, v114
	v_max_f32_e32 v34, v128, v128
	v_max_f32_e32 v33, v34, v33
	v_max_f32_e32 v34, v115, v115
	v_max_f32_e32 v35, v129, v129
	v_max_f32_e32 v34, v35, v34
	v_max3_f32 v32, v32, v33, v34
	v_max_f32_e32 v33, v110, v110
	v_max_f32_e32 v34, v126, v126
	v_max_f32_e32 v33, v34, v33
	v_max_f32_e32 v34, v111, v111
	v_max_f32_e32 v35, v127, v127
	v_max_f32_e32 v34, v35, v34
	v_max3_f32 v32, v32, v33, v34
	v_max_f32_e32 v33, v108, v108
	v_max_f32_e32 v34, v124, v124
	v_max_f32_e32 v33, v34, v33
	v_max_f32_e32 v34, v109, v109
	v_max_f32_e32 v35, v125, v125
	v_max_f32_e32 v34, v35, v34
	v_max3_f32 v32, v32, v33, v34
	v_max_f32_e32 v33, v106, v106
	v_max_f32_e32 v34, v122, v122
	v_max_f32_e32 v33, v34, v33
	v_max_f32_e32 v34, v107, v107
	v_max_f32_e32 v35, v123, v123
	v_max_f32_e32 v34, v35, v34
	v_max3_f32 v32, v32, v33, v34
	v_max_f32_e32 v33, v104, v104
	v_max_f32_e32 v34, v118, v118
	v_max_f32_e32 v33, v34, v33
	v_max_f32_e32 v34, v105, v105
	v_max_f32_e32 v35, v119, v119
	v_max_f32_e32 v34, v35, v34
	v_max3_f32 v32, v32, v33, v34
	v_max_f32_e32 v33, v102, v102
	v_max_f32_e32 v34, v112, v112
	v_max_f32_e32 v33, v34, v33
	v_max_f32_e32 v34, v103, v103
	v_max_f32_e32 v35, v113, v113
	v_max_f32_e32 v34, v35, v34
	v_max3_f32 v32, v32, v33, v34
	v_mov_b32_e32 v33, v32
	s_nop 1
	v_permlane32_swap_b32 v33, v32
	s_nop 1
	s_mov_b64 s[14:15], -1
	v_max_f32_e32 v32, v32, v32
	v_max_f32_e32 v33, v33, v33
	v_max_f32_e32 v163, v33, v32
	s_and_b64 vcc, exec, s[22:23]
	s_cbranch_vccz .LBB0_535
	s_mov_b32 s14, 0x41000000
	v_cmp_lt_f32_e32 vcc, s14, v163
	s_cbranch_vccz .LBB0_538
	v_max_f32_e32 v32, v163, v163
	v_max_f32_e32 v167, 0, v32
	v_exp_f32_e64 v184, -v167
	v_add_f32_e32 v148, v148, v167
	v_sub_f32_e32 v166, v132, v167
	v_sub_f32_e32 v165, v133, v167
	v_pk_mul_f32 v[62:63], v[30:31], v[184:185] op_sel_hi:[1,0]
	v_pk_mul_f32 v[60:61], v[28:29], v[184:185] op_sel_hi:[1,0]
	v_pk_mul_f32 v[58:59], v[26:27], v[184:185] op_sel_hi:[1,0]
	v_pk_mul_f32 v[56:57], v[24:25], v[184:185] op_sel_hi:[1,0]
	v_pk_mul_f32 v[54:55], v[22:23], v[184:185] op_sel_hi:[1,0]
	v_pk_mul_f32 v[52:53], v[20:21], v[184:185] op_sel_hi:[1,0]
	v_pk_mul_f32 v[50:51], v[18:19], v[184:185] op_sel_hi:[1,0]
	v_pk_mul_f32 v[48:49], v[16:17], v[184:185] op_sel_hi:[1,0]
	v_pk_mul_f32 v[46:47], v[14:15], v[184:185] op_sel_hi:[1,0]
	v_pk_mul_f32 v[44:45], v[12:13], v[184:185] op_sel_hi:[1,0]
	v_pk_mul_f32 v[42:43], v[10:11], v[184:185] op_sel_hi:[1,0]
	v_pk_mul_f32 v[40:41], v[8:9], v[184:185] op_sel_hi:[1,0]
	v_pk_mul_f32 v[38:39], v[6:7], v[184:185] op_sel_hi:[1,0]
	v_pk_mul_f32 v[36:37], v[4:5], v[184:185] op_sel_hi:[1,0]
	v_pk_mul_f32 v[34:35], v[2:3], v[184:185] op_sel_hi:[1,0]
	v_pk_mul_f32 v[32:33], v[0:1], v[184:185] op_sel_hi:[1,0]
	v_sub_f32_e32 v164, v130, v167
	v_sub_f32_e32 v162, v131, v167
	v_sub_f32_e32 v161, v128, v167
	v_sub_f32_e32 v160, v129, v167
	v_sub_f32_e32 v159, v126, v167
	v_sub_f32_e32 v158, v127, v167
	v_sub_f32_e32 v157, v124, v167
	v_sub_f32_e32 v156, v125, v167
	v_sub_f32_e32 v155, v122, v167
	v_sub_f32_e32 v154, v123, v167
	v_sub_f32_e32 v153, v118, v167
	v_sub_f32_e32 v152, v119, v167
	v_sub_f32_e32 v151, v112, v167
	v_sub_f32_e32 v150, v113, v167
	v_sub_f32_e32 v182, v120, v167
	v_sub_f32_e32 v181, v121, v167
	v_sub_f32_e32 v180, v116, v167
	v_sub_f32_e32 v179, v117, v167
	v_sub_f32_e32 v178, v114, v167
	v_sub_f32_e32 v177, v115, v167
	v_sub_f32_e32 v176, v110, v167
	v_sub_f32_e32 v175, v111, v167
	v_sub_f32_e32 v174, v108, v167
	v_sub_f32_e32 v173, v109, v167
	v_sub_f32_e32 v172, v106, v167
	v_sub_f32_e32 v171, v107, v167
	v_sub_f32_e32 v170, v104, v167
	v_sub_f32_e32 v169, v105, v167
	v_sub_f32_e32 v168, v102, v167
	v_sub_f32_e32 v167, v103, v167
	v_mul_f32_e32 v183, v146, v184
	s_mov_b64 s[14:15], 0

; #define FLAS __attribute__((address_space(3)))
; #define FA_SB() __builtin_amdgcn_sched_barrier(0)
; __device__ __forceinline__ unsigned cvtpk(float lo, float hi) { f32x2_t v = {lo, hi}; bf16x2_t b = __builtin_convertvector(v, bf16x2_t); return __builtin_bit_cast(unsigned, b); }
; template <int MODE> __device__ __forceinline__ void attn_unit(FLAS unsigned char* lds, const Unit u) {
;     ...
;             float ps = 0.f;
; #pragma unroll
;             for (int r = 0; r < 16; ++r) { p0[r] = __builtin_amdgcn_exp2f(p0[r]); p1[r] = __builtin_amdgcn_exp2f(p1[r]); ps += p0[r] + p1[r]; }
;             lsum += ps;
;             u32x4 pw[4];
;             pw[0] = (u32x4){cvtpk(p0[0], p0[1]), cvtpk(p0[2], p0[3]), cvtpk(p0[4], p0[5]), cvtpk(p0[6], p0[7])};
;             pw[1] = (u32x4){cvtpk(p0[8], p0[9]), cvtpk(p0[10], p0[11]), cvtpk(p0[12], p0[13]), cvtpk(p0[14], p0[15])};
;             pw[2] = (u32x4){cvtpk(p1[0], p1[1]), cvtpk(p1[2], p1[3]), cvtpk(p1[4], p1[5]), cvtpk(p1[6], p1[7])};
;             pw[3] = (u32x4){cvtpk(p1[8], p1[9]), cvtpk(p1[10], p1[11]), cvtpk(p1[12], p1[13]), cvtpk(p1[14], p1[15])};
;             FA_SB();
; #pragma unroll
;             for (int s = 0; s < 4; ++s) {
;                 if (s < 3) {
; #pragma unroll
;                     for (int db = 0; db < NDB; ++db) vf[(s + 1) & 1][db] = *(const FLAS u32x4*)(vb + db * 32 * VPITCH + (s + 1) * 32); }
; #pragma unroll
;                 for (int db = 0; db < NDB; ++db) o[db] = __builtin_amdgcn_mfma_f32_32x32x16_bf16(__builtin_bit_cast(bf16x8, vf[s & 1][db]), __builtin_bit_cast(bf16x8, pw[s]), o[db], 0, 0, 0);
;                 FA_SB();
;             }
.LBB0_538:
	v_exp_f32_e32 v132, v132
	v_exp_f32_e32 v133, v133
	v_exp_f32_e32 v130, v130
	v_exp_f32_e32 v131, v131
	v_add_f32_e32 v61, v132, v133
	v_cvt_pk_bf16_f32 v32, v132, v133
	v_exp_f32_e32 v128, v128
	v_add_f32_e32 v61, v130, v61
	v_exp_f32_e32 v129, v129
	v_add_f32_e32 v61, v131, v61
	v_cvt_pk_bf16_f32 v33, v130, v131
	v_exp_f32_e32 v126, v126
	v_add_f32_e32 v61, v128, v61
	v_exp_f32_e32 v127, v127
	v_add_f32_e32 v61, v129, v61
	v_cvt_pk_bf16_f32 v34, v128, v129
	v_exp_f32_e32 v124, v124
	v_add_f32_e32 v61, v126, v61
	v_exp_f32_e32 v125, v125
	v_add_f32_e32 v61, v127, v61
	v_cvt_pk_bf16_f32 v35, v126, v127
	v_exp_f32_e32 v122, v122
	v_add_f32_e32 v61, v124, v61
	v_exp_f32_e32 v123, v123
	v_add_f32_e32 v61, v125, v61
	v_cvt_pk_bf16_f32 v36, v124, v125
	v_exp_f32_e32 v118, v118
	v_add_f32_e32 v61, v122, v61
	v_exp_f32_e32 v119, v119
	v_add_f32_e32 v61, v123, v61
	v_cvt_pk_bf16_f32 v37, v122, v123
	v_exp_f32_e32 v112, v112
	v_add_f32_e32 v61, v118, v61
	v_exp_f32_e32 v113, v113
	v_add_f32_e32 v61, v119, v61
	v_cvt_pk_bf16_f32 v38, v118, v119
	v_exp_f32_e32 v120, v120
	v_add_f32_e32 v61, v112, v61
	v_exp_f32_e32 v121, v121
	v_add_f32_e32 v61, v113, v61
	v_cvt_pk_bf16_f32 v39, v112, v113
	v_exp_f32_e32 v116, v116
	v_add_f32_e32 v61, v120, v61
	v_exp_f32_e32 v117, v117
	v_add_f32_e32 v61, v121, v61
	v_cvt_pk_bf16_f32 v40, v120, v121
	v_exp_f32_e32 v114, v114
	v_add_f32_e32 v61, v116, v61
	v_exp_f32_e32 v115, v115
	v_add_f32_e32 v61, v117, v61
	v_cvt_pk_bf16_f32 v41, v116, v117
	v_exp_f32_e32 v110, v110
	v_add_f32_e32 v61, v114, v61
	v_exp_f32_e32 v111, v111
	v_add_f32_e32 v61, v115, v61
	v_cvt_pk_bf16_f32 v42, v114, v115
	v_exp_f32_e32 v108, v108
	v_add_f32_e32 v61, v110, v61
	v_exp_f32_e32 v109, v109
	v_add_f32_e32 v61, v111, v61
	v_cvt_pk_bf16_f32 v43, v110, v111
	v_exp_f32_e32 v106, v106
	v_add_f32_e32 v61, v108, v61
	v_exp_f32_e32 v107, v107
	v_add_f32_e32 v61, v109, v61
	v_cvt_pk_bf16_f32 v44, v108, v109
	v_exp_f32_e32 v104, v104
	v_add_f32_e32 v61, v106, v61
	v_exp_f32_e32 v105, v105
	v_add_f32_e32 v61, v107, v61
	v_cvt_pk_bf16_f32 v45, v106, v107
	v_exp_f32_e32 v102, v102
	v_add_f32_e32 v61, v104, v61
	v_exp_f32_e32 v103, v103
	v_add_f32_e32 v61, v105, v61
	v_cvt_pk_bf16_f32 v46, v104, v105
	v_add_f32_e32 v61, v102, v61
	v_add_f32_e32 v61, v103, v61
	v_cvt_pk_bf16_f32 v47, v102, v103
	s_waitcnt lgkmcnt(1)
	s_setprio 1
	v_mfma_f32_32x32x16_bf16 v[0:15], v[92:95], v[32:35], v[0:15]
	ds_read_b128 v[48:51], v149 offset:16416
	ds_read_b128 v[52:55], v149 offset:21024
	s_waitcnt lgkmcnt(2)
	v_mfma_f32_32x32x16_bf16 v[16:31], v[88:91], v[32:35], v[16:31]
	s_waitcnt lgkmcnt(1)
	v_mfma_f32_32x32x16_bf16 v[0:15], v[48:51], v[36:39], v[0:15]
	ds_read_b128 v[32:35], v149 offset:16448
	ds_read_b128 v[48:51], v149 offset:21056
	s_waitcnt lgkmcnt(2)
	v_mfma_f32_32x32x16_bf16 v[16:31], v[52:55], v[36:39], v[16:31]
	s_waitcnt lgkmcnt(1)
	v_mfma_f32_32x32x16_bf16 v[0:15], v[32:35], v[40:43], v[0:15]
	ds_read_b128 v[32:35], v149 offset:16480
	ds_read_b128 v[36:39], v149 offset:21088
	s_waitcnt lgkmcnt(2)
	v_mfma_f32_32x32x16_bf16 v[16:31], v[48:51], v[40:43], v[16:31]
	s_waitcnt lgkmcnt(1)
	v_mfma_f32_32x32x16_bf16 v[0:15], v[32:35], v[44:47], v[0:15]
	s_waitcnt lgkmcnt(0)
	v_mfma_f32_32x32x16_bf16 v[16:31], v[36:39], v[44:47], v[16:31]
	s_setprio 0
	v_add_f32_e32 v146, v146, v61
	s_mov_b64 s[22:23], 0
